# MLA loop: dead s_mov/s_nop removed, 0+x adds folded, lgkmcnt waits merged pairwise, LDS-DMA issue block merged (voffset regs, m0 direct)
# speedup vs baseline: 1.0554x; 1.0056x over previous
.LBB0_493:
	v_lshlrev_b32_e32 v34, 10, v0
	v_or_b32_e32 v1, v34, v172
	v_add_u32_e32 v0, 0, v1
	s_waitcnt vmcnt(5)
	s_waitcnt vmcnt(4)
	s_waitcnt vmcnt(3)
	s_waitcnt vmcnt(2)
	s_waitcnt vmcnt(1)
	s_waitcnt vmcnt(0)
	ds_read_b128 v[18:21], v0
	ds_read_b128 v[2:5], v0 offset:512
	s_waitcnt lgkmcnt(0)
	v_mfma_f32_32x32x16_bf16 v[2:17], v[2:5], v[118:121], 0
	ds_read_b128 v[36:39], v0 offset:2048
	ds_read_b128 v[22:25], v0 offset:2560
	s_lshl_b32 s9, s42, 8
	s_lshl_b32 s34, s3, 5
	s_lshl_b32 s10, s10, 10
	s_add_i32 s6, s34, s9
	s_lshl_b32 s11, s2, 6
	s_lshl_b32 s46, s42, 2
	s_waitcnt lgkmcnt(0)
	v_mfma_f32_32x32x16_bf16 v[2:17], v[22:25], v[114:117], v[2:17]
	ds_read_b128 v[40:43], v0 offset:4096
	ds_read_b128 v[22:25], v0 offset:4608
	s_and_b32 s45, s10, 0x7fffe000
	s_ashr_i32 s27, s6, 6
	s_and_b32 s35, s11, 0x1c0
	s_add_i32 s47, s46, 4
	s_add_i32 s45, s45, s9
	s_waitcnt lgkmcnt(0)
	v_mfma_f32_32x32x16_bf16 v[2:17], v[22:25], v[110:113], v[2:17]
	ds_read_b128 v[44:47], v0 offset:6144
	ds_read_b128 v[22:25], v0 offset:6656
	s_waitcnt lgkmcnt(0)
	v_mfma_f32_32x32x16_bf16 v[2:17], v[22:25], v[106:109], v[2:17]
	ds_read_b128 v[48:51], v0 offset:8192
	ds_read_b128 v[22:25], v0 offset:8704
	s_waitcnt lgkmcnt(0)
	v_mfma_f32_32x32x16_bf16 v[2:17], v[22:25], v[102:105], v[2:17]
	ds_read_b128 v[52:55], v0 offset:10240
	ds_read_b128 v[22:25], v0 offset:10752
	s_waitcnt lgkmcnt(0)
	v_mfma_f32_32x32x16_bf16 v[2:17], v[22:25], v[98:101], v[2:17]
	v_mfma_f32_32x32x16_bf16 v[18:33], v[18:21], v[118:121], 0
	v_mov_b32_e32 v0, v173
	s_mov_b64 s[10:11], -1
	s_cmp_lt_i32 s27, 0
	v_mfma_f32_32x32x16_bf16 v[18:33], v[36:39], v[114:117], v[18:33]
	v_mfma_f32_32x32x16_bf16 v[18:33], v[40:43], v[110:113], v[18:33]
	v_mfma_f32_32x32x16_bf16 v[18:33], v[44:47], v[106:109], v[18:33]
	v_mfma_f32_32x32x16_bf16 v[18:33], v[48:51], v[102:105], v[18:33]
	v_mfma_f32_32x32x16_bf16 v[18:33], v[52:55], v[98:101], v[18:33]
	s_cbranch_scc1 .LBB0_520
	s_cmp_lt_u32 s27, 2
	s_mov_b32 s10, 2
	s_cbranch_scc1 .LBB0_502
	v_add_u32_e32 v218, 0x1000, v170
	v_add_u32_e32 v219, 0x2000, v170
	s_lshl_b32 s9, s3, 10
	s_and_b32 s28, s9, 0xc00
	s_add_u32 s29, s18, s40
	s_addc_u32 s30, s19, s41
	s_add_u32 s31, s38, s44
	s_addc_u32 s33, s39, s43
	v_add_u32_e32 v139, v172, v34
	v_mov_b32_e32 v138, 0
	s_mov_b32 s48, 2
	s_mov_b32 s49, 4
	s_mov_b32 s50, 0
	s_mov_b32 s51, 0
	v_mov_b32_e32 v66, v0
	v_mov_b32_e32 v67, v0
	v_mov_b32_e32 v68, v0
	v_mov_b32_e32 v69, v0
	v_mov_b32_e32 v70, v0
	v_mov_b32_e32 v71, v0
	v_mov_b32_e32 v72, v0
	v_mov_b32_e32 v73, v0
	v_mov_b32_e32 v74, v0
	v_mov_b32_e32 v75, v0
	v_mov_b32_e32 v76, v0
	v_mov_b32_e32 v77, v0
	v_mov_b32_e32 v78, v0
	v_mov_b32_e32 v79, v0
	v_mov_b32_e32 v80, v0
	v_mov_b32_e32 v81, v0
	v_mov_b32_e32 v82, v0
	v_mov_b32_e32 v83, v0
	v_mov_b32_e32 v84, v0
	v_mov_b32_e32 v85, v0
	v_mov_b32_e32 v86, v0
	v_mov_b32_e32 v87, v0
	v_mov_b32_e32 v88, v0
	v_mov_b32_e32 v89, v0
	v_mov_b32_e32 v90, v0
	v_mov_b32_e32 v91, v0
	v_mov_b32_e32 v92, v0
	v_mov_b32_e32 v93, v0
	v_mov_b32_e32 v94, v0
	v_mov_b32_e32 v95, v0
	v_mov_b32_e32 v96, v0
	v_mov_b32_e32 v97, v0
.LBB0_496:
	s_mul_hi_u32 s9, s49, 0xaaaaaaab
	s_lshr_b32 s9, s9, 2
	s_mul_i32 s9, s9, 0x1e000
	s_sub_i32 s9, s28, s9
	s_cmp_ge_u32 s51, s46
	s_waitcnt vmcnt(0) lgkmcnt(0)
	s_barrier
	s_cselect_b64 s[10:11], -1, 0
	s_or_b64 s[10:11], s[4:5], s[10:11]
	s_and_b64 vcc, exec, s[10:11]
	s_cbranch_vccnz .LBB0_500
	s_add_u32 s10, s31, s28
	s_addc_u32 s11, s33, 0
	s_add_u32 s10, s10, 0x180c000
	s_addc_u32 s11, s11, 0
	s_add_i32 s13, s50, s9
	s_add_i32 m0, s13, 0x14000
	s_add_u32 s14, s29, s28
	s_addc_u32 s15, s30, 0
	global_load_lds_dwordx4 v170, s[10:11]
	s_add_i32 m0, s13, 0x15000
	s_add_u32 s14, s14, 0xb708000
	s_addc_u32 s15, s15, 0
	global_load_lds_dwordx4 v218, s[10:11]
	s_add_i32 m0, s13, 0x16000
	s_nop 0
	global_load_lds_dwordx4 v219, s[10:11]
	s_add_i32 m0, s13, 0x17000
	s_nop 0
	global_load_lds_dwordx4 v170, s[14:15]
	s_add_i32 m0, s13, 0x18000
	s_add_u32 s10, s10, 0x3000
	s_addc_u32 s11, s11, 0
	global_load_lds_dwordx4 v218, s[14:15]
	s_add_i32 m0, s13, 0x19000
	s_add_u32 s14, s14, 0x2000
	s_addc_u32 s15, s15, 0
	global_load_lds_dwordx4 v170, s[10:11]
	s_add_i32 m0, s13, 0x1a000
	s_nop 0
	global_load_lds_dwordx4 v218, s[10:11]
	s_add_i32 m0, s13, 0x1b000
	s_nop 0
	global_load_lds_dwordx4 v219, s[10:11]
	s_add_i32 m0, s13, 0x1c000
	s_nop 0
	global_load_lds_dwordx4 v170, s[14:15]
	s_add_i32 m0, s13, 0x1d000
	s_nop 0
	global_load_lds_dwordx4 v218, s[14:15]
.LBB0_500:
	s_mul_hi_u32 s9, s51, 0xaaaaaaab
	s_lshr_b32 s9, s9, 2
	s_mul_i32 s9, s9, 0xfffe2000
	s_add_i32 s9, s9, 0
	v_add_u32_e32 v141, s50, v139
	v_add_u32_e32 v140, s9, v141
	ds_read_b128 v[34:37], v140 offset:12288
	ds_read_b128 v[38:41], v140 offset:12800
	ds_read_b128 v[42:45], v140 offset:20480
	ds_read_b128 v[46:49], v140 offset:20992
	ds_read_b128 v[142:145], v140 offset:22528
	s_mul_hi_u32 s9, s48, 0xaaaaaaab
	s_lshr_b32 s9, s9, 2
	s_mul_i32 s9, s9, 0xfffe2000
	s_add_i32 s52, s9, 0
	v_exp_f32_e32 v18, v18
	v_exp_f32_e32 v19, v19
	v_exp_f32_e32 v20, v20
	v_exp_f32_e32 v21, v21
	v_exp_f32_e32 v22, v22
	v_exp_f32_e32 v23, v23
	v_exp_f32_e32 v24, v24
	v_exp_f32_e32 v25, v25
	v_add_f32_e32 v50, v20, v18
	v_add_f32_e32 v51, v21, v19
	v_add_f32_e32 v50, v22, v50
	v_add_f32_e32 v51, v23, v51
	v_cvt_pk_bf16_f32 v134, v18, v19
	v_cvt_pk_bf16_f32 v135, v20, v21
	v_cvt_pk_bf16_f32 v136, v22, v23
	v_add_f32_e32 v162, v25, v51
	v_add_f32_e32 v163, v24, v50
	v_cvt_pk_bf16_f32 v137, v24, v25
	s_waitcnt lgkmcnt(3)
	s_nop 0
	v_mfma_f32_32x32x16_bf16 v[66:81], v[34:37], v[134:137], v[66:81]
	ds_read_b128 v[146:149], v140 offset:14336
	v_exp_f32_e32 v26, v26
	v_exp_f32_e32 v27, v27
	v_mfma_f32_32x32x16_bf16 v[82:97], v[38:41], v[134:137], v[82:97]
	ds_read_b128 v[150:153], v140 offset:14848
	v_exp_f32_e32 v28, v28
	v_exp_f32_e32 v29, v29
	v_exp_f32_e32 v30, v30
	v_exp_f32_e32 v31, v31
	ds_read_b128 v[154:157], v140 offset:23040
	v_exp_f32_e32 v32, v32
	v_exp_f32_e32 v33, v33
	s_waitcnt lgkmcnt(4)
	v_mfma_f32_32x32x16_bf16 v[50:65], v[42:45], v[118:121], 0
	ds_read_b128 v[158:161], v140 offset:24576
	v_add_f32_e32 v163, v163, v26
	v_add_f32_e32 v162, v162, v27
	v_cvt_pk_bf16_f32 v130, v26, v27
	v_cvt_pk_bf16_f32 v131, v28, v29
	v_add_f32_e32 v163, v28, v163
	v_add_f32_e32 v162, v29, v162
	v_mfma_f32_32x32x16_bf16 v[34:49], v[46:49], v[118:121], 0
	s_waitcnt lgkmcnt(3)
	v_mfma_f32_32x32x16_bf16 v[50:65], v[142:145], v[114:117], v[50:65]
	ds_read_b128 v[142:145], v140 offset:25088
	v_add_f32_e32 v163, v163, v30
	v_add_f32_e32 v162, v162, v31
	v_cvt_pk_bf16_f32 v132, v30, v31
	v_cvt_pk_bf16_f32 v133, v32, v33
	v_add_f32_e32 v163, v32, v163
	v_add_f32_e32 v162, v33, v162
	v_mfma_f32_32x32x16_bf16 v[66:81], v[146:149], v[130:133], v[66:81]
	ds_read_b128 v[18:21], v140 offset:16384
	v_exp_f32_e32 v2, v2
	v_exp_f32_e32 v3, v3
	s_waitcnt lgkmcnt(3)
	v_mfma_f32_32x32x16_bf16 v[82:97], v[150:153], v[130:133], v[82:97]
	ds_read_b128 v[22:25], v140 offset:16896
	v_exp_f32_e32 v4, v4
	v_exp_f32_e32 v5, v5
	v_exp_f32_e32 v6, v6
	v_exp_f32_e32 v7, v7
	ds_read_b128 v[26:29], v140 offset:26624
	v_exp_f32_e32 v8, v8
	v_exp_f32_e32 v9, v9
	v_mfma_f32_32x32x16_bf16 v[34:49], v[154:157], v[114:117], v[34:49]
	ds_read_b128 v[30:33], v140 offset:27136
	v_add_f32_e32 v146, v163, v2
	v_add_f32_e32 v147, v162, v3
	v_cvt_pk_bf16_f32 v134, v2, v3
	v_cvt_pk_bf16_f32 v135, v4, v5
	v_add_f32_e32 v146, v4, v146
	v_add_f32_e32 v147, v5, v147
	s_waitcnt lgkmcnt(4)
	v_mfma_f32_32x32x16_bf16 v[50:65], v[158:161], v[110:113], v[50:65]
	v_mfma_f32_32x32x16_bf16 v[34:49], v[142:145], v[110:113], v[34:49]
	ds_read_b128 v[142:145], v140 offset:28672
	v_add_f32_e32 v146, v146, v6
	v_add_f32_e32 v147, v147, v7
	v_cvt_pk_bf16_f32 v136, v6, v7
	v_cvt_pk_bf16_f32 v137, v8, v9
	v_add_f32_e32 v146, v8, v146
	v_add_f32_e32 v147, v9, v147
	s_waitcnt lgkmcnt(3)
	v_mfma_f32_32x32x16_bf16 v[66:81], v[18:21], v[134:137], v[66:81]
	ds_read_b128 v[18:21], v140 offset:18432
	v_exp_f32_e32 v10, v10
	v_exp_f32_e32 v11, v11
	v_mfma_f32_32x32x16_bf16 v[82:97], v[22:25], v[134:137], v[82:97]
	ds_read_b128 v[22:25], v140 offset:18944
	v_exp_f32_e32 v12, v12
	v_exp_f32_e32 v13, v13
	v_exp_f32_e32 v14, v14
	v_exp_f32_e32 v15, v15
	s_waitcnt lgkmcnt(3)
	v_mfma_f32_32x32x16_bf16 v[50:65], v[26:29], v[106:109], v[50:65]
	ds_read_b128 v[26:29], v140 offset:29184
	v_exp_f32_e32 v16, v16
	v_exp_f32_e32 v17, v17
	v_mfma_f32_32x32x16_bf16 v[34:49], v[30:33], v[106:109], v[34:49]
	ds_read_b128 v[30:33], v140 offset:30720
	v_add_f32_e32 v134, v146, v10
	v_add_f32_e32 v135, v147, v11
	v_cvt_pk_bf16_f32 v130, v10, v11
	v_cvt_pk_bf16_f32 v131, v12, v13
	v_add_f32_e32 v134, v12, v134
	v_add_f32_e32 v135, v13, v135
	s_waitcnt lgkmcnt(3)
	v_mfma_f32_32x32x16_bf16 v[50:65], v[142:145], v[102:105], v[50:65]
	ds_read_b128 v[142:145], v140 offset:31232
	v_add_f32_e32 v134, v134, v14
	v_add_f32_e32 v135, v135, v15
	v_cvt_pk_bf16_f32 v132, v14, v15
	v_cvt_pk_bf16_f32 v133, v16, v17
	v_add_f32_e32 v134, v16, v134
	v_add_f32_e32 v136, v17, v135
	v_mfma_f32_32x32x16_bf16 v[66:81], v[18:21], v[130:133], v[66:81]
	s_waitcnt lgkmcnt(2)
	v_mfma_f32_32x32x16_bf16 v[82:97], v[22:25], v[130:133], v[82:97]
	v_mfma_f32_32x32x16_bf16 v[34:49], v[26:29], v[102:105], v[34:49]
	s_waitcnt lgkmcnt(0)
	v_mfma_f32_32x32x16_bf16 v[50:65], v[30:33], v[98:101], v[50:65]
	v_mfma_f32_32x32x16_bf16 v[34:49], v[142:145], v[98:101], v[34:49]
	v_add_u32_e32 v135, s52, v141
	ds_read_b128 v[2:5], v140 offset:32768
	ds_read_b128 v[6:9], v140 offset:33280
	ds_read_b128 v[10:13], v135 offset:40960
	ds_read_b128 v[14:17], v135 offset:41472
	ds_read_b128 v[142:145], v135 offset:43008
	s_nop 3
	v_exp_f32_e32 v50, v50
	v_exp_f32_e32 v51, v51
	v_exp_f32_e32 v52, v52
	v_exp_f32_e32 v53, v53
	v_exp_f32_e32 v54, v54
	v_exp_f32_e32 v55, v55
	v_exp_f32_e32 v56, v56
	v_exp_f32_e32 v57, v57
	v_add_f32_e32 v18, v52, v50
	v_add_f32_e32 v19, v53, v51
	v_add_f32_e32 v18, v54, v18
	v_add_f32_e32 v19, v55, v19
	v_cvt_pk_bf16_f32 v130, v50, v51
	v_cvt_pk_bf16_f32 v131, v52, v53
	v_cvt_pk_bf16_f32 v132, v54, v55
	v_add_f32_e32 v137, v57, v19
	v_add_f32_e32 v141, v56, v18
	v_cvt_pk_bf16_f32 v133, v56, v57
	s_waitcnt lgkmcnt(3)
	s_nop 0
	v_mfma_f32_32x32x16_bf16 v[66:81], v[2:5], v[130:133], v[66:81]
	ds_read_b128 v[146:149], v140 offset:34816
	v_exp_f32_e32 v58, v58
	v_exp_f32_e32 v59, v59
	v_mfma_f32_32x32x16_bf16 v[82:97], v[6:9], v[130:133], v[82:97]
	ds_read_b128 v[150:153], v140 offset:35328
	v_exp_f32_e32 v60, v60
	v_exp_f32_e32 v61, v61
	v_exp_f32_e32 v62, v62
	v_exp_f32_e32 v63, v63
	s_waitcnt lgkmcnt(3)
	v_mfma_f32_32x32x16_bf16 v[18:33], v[10:13], v[118:121], 0
	ds_read_b128 v[154:157], v135 offset:43520
	v_exp_f32_e32 v64, v64
	v_exp_f32_e32 v65, v65
	v_mfma_f32_32x32x16_bf16 v[2:17], v[14:17], v[118:121], 0
	ds_read_b128 v[158:161], v135 offset:45056
	v_add_f32_e32 v141, v141, v58
	v_add_f32_e32 v137, v137, v59
	v_cvt_pk_bf16_f32 v122, v58, v59
	v_cvt_pk_bf16_f32 v123, v60, v61
	v_add_f32_e32 v141, v60, v141
	v_add_f32_e32 v137, v61, v137
	s_waitcnt lgkmcnt(3)
	v_mfma_f32_32x32x16_bf16 v[18:33], v[142:145], v[114:117], v[18:33]
	ds_read_b128 v[142:145], v135 offset:45568
	v_add_f32_e32 v141, v141, v62
	v_add_f32_e32 v137, v137, v63
	v_cvt_pk_bf16_f32 v124, v62, v63
	v_cvt_pk_bf16_f32 v125, v64, v65
	v_add_f32_e32 v141, v64, v141
	v_add_f32_e32 v137, v65, v137
	v_mfma_f32_32x32x16_bf16 v[66:81], v[146:149], v[122:125], v[66:81]
	ds_read_b128 v[50:53], v140 offset:36864
	v_exp_f32_e32 v34, v34
	v_exp_f32_e32 v35, v35
	s_waitcnt lgkmcnt(3)
	v_mfma_f32_32x32x16_bf16 v[82:97], v[150:153], v[122:125], v[82:97]
	ds_read_b128 v[54:57], v140 offset:37376
	v_exp_f32_e32 v36, v36
	v_exp_f32_e32 v37, v37
	v_exp_f32_e32 v38, v38
	v_exp_f32_e32 v39, v39
	v_mfma_f32_32x32x16_bf16 v[2:17], v[154:157], v[114:117], v[2:17]
	ds_read_b128 v[58:61], v135 offset:47104
	v_exp_f32_e32 v40, v40
	v_exp_f32_e32 v41, v41
	s_waitcnt lgkmcnt(3)
	v_mfma_f32_32x32x16_bf16 v[18:33], v[158:161], v[110:113], v[18:33]
	ds_read_b128 v[62:65], v135 offset:47616
	v_add_f32_e32 v141, v141, v34
	v_add_f32_e32 v137, v137, v35
	v_cvt_pk_bf16_f32 v130, v34, v35
	v_cvt_pk_bf16_f32 v131, v36, v37
	v_add_f32_e32 v141, v36, v141
	v_add_f32_e32 v137, v37, v137
	v_mfma_f32_32x32x16_bf16 v[2:17], v[142:145], v[110:113], v[2:17]
	ds_read_b128 v[142:145], v135 offset:49152
	v_add_f32_e32 v141, v141, v38
	v_add_f32_e32 v137, v137, v39
	v_cvt_pk_bf16_f32 v132, v38, v39
	v_cvt_pk_bf16_f32 v133, v40, v41
	v_add_f32_e32 v141, v40, v141
	v_add_f32_e32 v137, v41, v137
	s_waitcnt lgkmcnt(3)
	v_mfma_f32_32x32x16_bf16 v[66:81], v[50:53], v[130:133], v[66:81]
	ds_read_b128 v[50:53], v140 offset:38912
	v_exp_f32_e32 v42, v42
	v_exp_f32_e32 v43, v43
	v_mfma_f32_32x32x16_bf16 v[82:97], v[54:57], v[130:133], v[82:97]
	ds_read_b128 v[54:57], v140 offset:39424
	v_exp_f32_e32 v44, v44
	v_exp_f32_e32 v45, v45
	v_exp_f32_e32 v46, v46
	v_exp_f32_e32 v47, v47
	s_waitcnt lgkmcnt(3)
	v_mfma_f32_32x32x16_bf16 v[18:33], v[58:61], v[106:109], v[18:33]
	ds_read_b128 v[58:61], v135 offset:49664
	v_exp_f32_e32 v48, v48
	v_exp_f32_e32 v49, v49
	v_mfma_f32_32x32x16_bf16 v[2:17], v[62:65], v[106:109], v[2:17]
	ds_read_b128 v[62:65], v135 offset:51200
	v_add_f32_e32 v130, v141, v42
	v_add_f32_e32 v131, v137, v43
	v_cvt_pk_bf16_f32 v122, v42, v43
	v_cvt_pk_bf16_f32 v123, v44, v45
	v_add_f32_e32 v137, v44, v130
	v_add_f32_e32 v140, v45, v131
	s_waitcnt lgkmcnt(3)
	v_mfma_f32_32x32x16_bf16 v[18:33], v[142:145], v[102:105], v[18:33]
	ds_read_b128 v[130:133], v135 offset:51712
	v_add_f32_e32 v135, v137, v46
	v_add_f32_e32 v137, v140, v47
	v_cvt_pk_bf16_f32 v124, v46, v47
	v_cvt_pk_bf16_f32 v125, v48, v49
	v_add_f32_e32 v135, v48, v135
	v_add_f32_e32 v137, v49, v137
	v_mfma_f32_32x32x16_bf16 v[66:81], v[50:53], v[122:125], v[66:81]
	s_waitcnt lgkmcnt(2)
	v_mfma_f32_32x32x16_bf16 v[82:97], v[54:57], v[122:125], v[82:97]
	v_mfma_f32_32x32x16_bf16 v[2:17], v[58:61], v[102:105], v[2:17]
	s_waitcnt lgkmcnt(0)
	v_mfma_f32_32x32x16_bf16 v[18:33], v[62:65], v[98:101], v[18:33]
	v_mfma_f32_32x32x16_bf16 v[2:17], v[130:133], v[98:101], v[2:17]
	s_add_i32 s48, s48, 2
	s_add_i32 s9, s51, 2
	s_add_u32 s29, s29, 0x4000
	s_addc_u32 s30, s30, 0
	v_add_f32_e64 v34, v136, v134
	v_add_f32_e64 v35, v137, v135
	s_add_u32 s31, s31, 0x6000
	v_add_f32_e32 v34, v138, v34
	s_addc_u32 s33, s33, 0
	s_add_i32 s49, s49, 2
	s_add_i32 s50, s50, 0xa000
	s_add_i32 s10, s51, 4
	s_cmp_le_i32 s10, s27
	v_add_f32_e32 v138, v34, v35
	s_cbranch_scc0 .LBB0_503
	s_mov_b32 s51, s9
	s_branch .LBB0_496
